# attention-B schedule S2: all 32 WGs of an XCD stream the same (batch,head) K/V; row blocks w / 31-w per head
# speedup vs baseline: 1.0066x; 1.0066x over previous
; __device__ __forceinline__ void attn_phase(LAS unsigned char* lds, unsigned char* ws, int l) {
;     ...
;     for (int vb = blockIdx.x; vb < 256; vb += gridDim.x) {
;         const int v2 = (vb & 7) * 32 + (vb >> 3);
;         const int j = v2 & 7, h = (v2 >> 3) & 7, b = v2 >> 6;
;         const bf16_t* base = P + (size_t)b * SEQ * INW;
;         for (int i = 0; i < 2; ++i) { const int qblk = i ? (15 - j) : j;
;             for (int cmb = 0; cmb < 4; ++cmb) { const int mp = cmb >> 1, sub = cmb & 1;
;                 attn_b_unit(lds, P + P_QB + (size_t)((b * 8 + h) * 2 + mp) * SEQ * 128, P + P_KB + (size_t)((b * 8 + h) * 2 + mp) * SEQ * 128, P + P_VB + (size_t)((b * 8 + h) * 2) * SEQ * 128,
;                             O12 + (size_t)b * SEQ * 4096 + mp * 2048 + h * 256, (qblk * 2 + sub) * 128); }
;             __builtin_amdgcn_fence(__ATOMIC_RELEASE, "workgroup"); __syncthreads(); __builtin_amdgcn_fence(__ATOMIC_ACQUIRE, "workgroup");
;             int tid = threadIdx.x; asm volatile("" : "+v"(tid));
;             const int lane = tid & 63, wv = tid >> 6;
;             const float lam_init = 0.8f - 0.6f * expf(-0.3f * (float)l);
.LBB0_247:
	v_readlane_b32 s0, v253, 18
	v_readlane_b32 s1, v253, 19
	s_andn2_b64 vcc, exec, s[0:1]
	s_cbranch_vccnz .LBB0_289
	v_cvt_f32_u32_e32 v0, s40
	s_lshl_b32 s4, s40, 7
	s_lshl_b32 s0, s40, 8
	s_mov_b32 s1, s5
	v_mul_f32_e32 v0, 0xbe99999a, v0
	v_mul_f32_e32 v2, 0x3fb8aa3b, v0
	v_fma_f32 v3, v0, s83, -v2
	v_rndne_f32_e32 v4, v2
	v_fmac_f32_e32 v3, 0x32a5705f, v0
	v_sub_f32_e32 v2, v2, v4
	v_add_f32_e32 v2, v2, v3
	v_cvt_i32_f32_e32 v4, v4
	v_exp_f32_e32 v2, v2
	v_cmp_ngt_f32_e32 vcc, s84, v0
	s_lshl_b64 s[6:7], s[4:5], 2
	s_lshl_b64 s[30:31], s[0:1], 2
	v_ldexp_f32 v2, v2, v4
	v_cndmask_b32_e32 v2, 0, v2, vcc
	v_cmp_nlt_f32_e32 vcc, s85, v0
	v_readlane_b32 s4, v254, 46
	s_mov_b32 s27, s2
	v_cndmask_b32_e32 v0, v231, v2, vcc
	v_fmamk_f32 v130, v0, 0xbf19999a, v224
	v_sub_f32_e32 v114, 1.0, v130
	v_mov_b32_e32 v116, v114
	v_mov_b32_e32 v117, v114
	s_mov_b32 s98, 0
.LBB0_249:
	s_and_b32 s0, s27, 7
	s_lshr_b32 s14, s27, 3
	s_and_b32 s15, s0, 1
	s_lshl_b32 s15, s15, 2
	s_add_i32 s15, s15, s98
	s_lshr_b32 s0, s0, 1
	s_sub_i32 s13, 31, s14
	s_bitcmp1_b32 s98, 0
	s_cselect_b32 s14, s13, s14
	s_lshl_b32 s45, s14, 7
	s_lshl_b32 s20, s0, 4
	s_lshl_b32 s8, s15, 1
	s_or_b32 s40, s8, s20
	s_ashr_i32 s1, s0, 31
	s_ashr_i32 s41, s40, 31
	s_lshl_b64 s[34:35], s[0:1], 12
	s_lshl_b64 s[8:9], s[40:41], 20
	v_readlane_b32 s21, v252, 8
	s_add_u32 s42, s21, s8
	v_readlane_b32 s8, v252, 9
	s_addc_u32 s43, s8, s9
	s_lshl_b64 s[0:1], s[0:1], 25
	s_add_u32 s0, s54, s0
	s_addc_u32 s1, s55, s1
	s_lshl_b32 s8, s15, 9
	s_add_u32 s41, s0, s8
	s_addc_u32 s44, s1, 0
	s_mov_b32 s8, s15
	s_lshl_b32 s0, s8, 1
	s_or_b32 s46, s20, s0
	s_ashr_i32 s47, s46, 31
	s_xor_b32 s93, s45, 0xf00
	s_lshl_b64 s[0:1], s[46:47], 20
	v_readlane_b32 s9, v254, 44
	s_add_u32 s58, s9, s0
	v_readlane_b32 s0, v254, 45
	s_addc_u32 s59, s0, s1
	s_lshl_b32 s0, s8, 9
	v_readlane_b32 s1, v253, 44
	s_add_u32 s66, s1, s0
	v_readlane_b32 s1, v253, 45
	s_addc_u32 s67, s1, 0
	s_add_u32 s8, s54, s0
	s_addc_u32 s9, s55, 0
	s_mov_b64 s[0:1], -1

; #define LAS __attribute__((address_space(3)))
; __device__ __forceinline__ unsigned pk2(float lo, float hi) { f32x2 v = {lo, hi}; bf16x2_t b = __builtin_convertvector(v, bf16x2_t); return __builtin_bit_cast(unsigned, b); }
; __device__ __forceinline__ void attn_b_unit(LAS unsigned char* lds, const bf16_t* __restrict__ Q, const bf16_t* __restrict__ K, const bf16_t* __restrict__ V, bf16_t* __restrict__ O, int q0) {
;     ...
;     LAS float* wsf = (LAS float*)(lds + WOFF + wid * 128);
;     if (hi == 0) wsf[r32] = 1.0f / ltot;
;     asm volatile("s_waitcnt lgkmcnt(0)" ::: "memory");
;     f32x4 fv[4];
; #pragma unroll
;     for (int gq = 0; gq < 4; ++gq) fv[gq] = *(const LAS f32x4*)(wsf + 8 * gq + 4 * hi);
;     asm volatile("" ::: "memory");
;     LAS bf16_t* stg = (LAS bf16_t*)(lds + POFF + wid * 4096);
; #pragma unroll
;     for (int hf = 0; hf < 2; ++hf) {
; #pragma unroll
;         for (int d2 = 0; d2 < 2; ++d2)
; #pragma unroll
;             for (int r = 0; r < 16; ++r) { const int orow = (r & 3) + 8 * (r >> 2) + 4 * hi;
;                 const float v = o[2 * hf + d2][r] * fv[r >> 2][r & 3];
;                 stg[orow * 64 + d2 * 32 + r32] = (bf16_t)(pk2(v, 0.f) & 0xffffu); }
;         asm volatile("s_waitcnt lgkmcnt(0)" ::: "memory");
; #pragma unroll
;         for (int i = 0; i < 4; ++i) { const int row = i * 8 + (lane >> 3), ch = lane & 7;
;             const u32x4 v = *(const LAS u32x4*)(stg + row * 64 + ch * 8);
;             *(u32x4*)(O + (size_t)(qw + row) * 4096 + g * 128 + hf * 64 + ch * 8) = v; }
.LBB0_251:
	s_or_b64 exec, exec, s[36:37]
	s_lshl_b32 s14, s95, 12
	s_add_u32 s14, s41, s14
	s_waitcnt lgkmcnt(0)
	s_addc_u32 s15, s44, 0
	ds_read_b128 v[68:71], v136
	ds_read_b128 v[72:75], v136 offset:32
	ds_read_b128 v[76:79], v136 offset:64
	ds_read_b128 v[80:83], v136 offset:96
	v_lshlrev_b32_e32 v0, 1, v134
	v_ashrrev_i32_e32 v67, 31, v66
	s_add_i32 s97, s97, 0x18000
	v_and_b32_e32 v0, 0x70, v0
	v_lshl_add_u64 v[66:67], v[66:67], 1, s[14:15]
	v_lshlrev_b32_e32 v84, 1, v133
	v_add_u32_e32 v86, s97, v0
	v_lshl_add_u64 v[66:67], v[66:67], 0, v[0:1]
	s_waitcnt lgkmcnt(0)
	v_mul_f32_e32 v0, v50, v68
	v_lshlrev_b32_e32 v50, 9, v115
	v_cvt_pk_bf16_f32 v0, v0, s0
	v_add3_u32 v50, s97, v84, v50
	ds_write_b16 v50, v0
	v_mul_f32_e32 v0, v51, v69
	v_cvt_pk_bf16_f32 v0, v0, s0
	ds_write_b16 v50, v0 offset:128
	v_mul_f32_e32 v0, v52, v70
	v_cvt_pk_bf16_f32 v0, v0, s0
	ds_write_b16 v50, v0 offset:256
	v_mul_f32_e32 v0, v53, v71
	v_cvt_pk_bf16_f32 v0, v0, s0
	ds_write_b16 v50, v0 offset:384
	v_mul_f32_e32 v0, v54, v72
	v_cvt_pk_bf16_f32 v0, v0, s0
	ds_write_b16 v50, v0 offset:1024
	v_mul_f32_e32 v0, v55, v73
	v_cvt_pk_bf16_f32 v0, v0, s0
	ds_write_b16 v50, v0 offset:1152
	v_mul_f32_e32 v0, v56, v74
	v_cvt_pk_bf16_f32 v0, v0, s0
	ds_write_b16 v50, v0 offset:1280
	v_mul_f32_e32 v0, v57, v75
	v_cvt_pk_bf16_f32 v0, v0, s0
	ds_write_b16 v50, v0 offset:1408
	v_mul_f32_e32 v0, v58, v76
	v_cvt_pk_bf16_f32 v0, v0, s0
	ds_write_b16 v50, v0 offset:2048
	v_mul_f32_e32 v0, v59, v77
	v_cvt_pk_bf16_f32 v0, v0, s0
	ds_write_b16 v50, v0 offset:2176
	v_mul_f32_e32 v0, v60, v78
	v_cvt_pk_bf16_f32 v0, v0, s0
	ds_write_b16 v50, v0 offset:2304
	v_mul_f32_e32 v0, v61, v79
	v_cvt_pk_bf16_f32 v0, v0, s0
	ds_write_b16 v50, v0 offset:2432
	v_mul_f32_e32 v0, v62, v80
	v_cvt_pk_bf16_f32 v0, v0, s0
	ds_write_b16 v50, v0 offset:3072
	v_mul_f32_e32 v0, v63, v81
	v_cvt_pk_bf16_f32 v0, v0, s0
	ds_write_b16 v50, v0 offset:3200
	v_mul_f32_e32 v0, v64, v82
	v_cvt_pk_bf16_f32 v0, v0, s0
	ds_write_b16 v50, v0 offset:3328
	v_mul_f32_e32 v0, v65, v83
	v_cvt_pk_bf16_f32 v0, v0, s0
	ds_write_b16 v50, v0 offset:3456
	v_mul_f32_e32 v0, v34, v68
	v_cvt_pk_bf16_f32 v0, v0, s0
	ds_write_b16 v50, v0 offset:64
	v_mul_f32_e32 v0, v35, v69
	v_cvt_pk_bf16_f32 v0, v0, s0
	ds_write_b16 v50, v0 offset:192
	v_mul_f32_e32 v0, v36, v70
	v_cvt_pk_bf16_f32 v0, v0, s0
	ds_write_b16 v50, v0 offset:320
	v_mul_f32_e32 v0, v37, v71
	v_cvt_pk_bf16_f32 v0, v0, s0
	ds_write_b16 v50, v0 offset:448
	v_mul_f32_e32 v0, v38, v72
	v_cvt_pk_bf16_f32 v0, v0, s0
	ds_write_b16 v50, v0 offset:1088
	v_mul_f32_e32 v0, v39, v73
	v_cvt_pk_bf16_f32 v0, v0, s0
	ds_write_b16 v50, v0 offset:1216
	v_mul_f32_e32 v0, v40, v74
	v_cvt_pk_bf16_f32 v0, v0, s0
	ds_write_b16 v50, v0 offset:1344
	v_mul_f32_e32 v0, v41, v75
	v_cvt_pk_bf16_f32 v0, v0, s0
	ds_write_b16 v50, v0 offset:1472
	v_mul_f32_e32 v0, v42, v76
	v_cvt_pk_bf16_f32 v0, v0, s0
	ds_write_b16 v50, v0 offset:2112
	v_mul_f32_e32 v0, v43, v77
	v_cvt_pk_bf16_f32 v0, v0, s0
	ds_write_b16 v50, v0 offset:2240
	v_mul_f32_e32 v0, v44, v78
	v_cvt_pk_bf16_f32 v0, v0, s0
	ds_write_b16 v50, v0 offset:2368
	v_mul_f32_e32 v0, v45, v79
	v_cvt_pk_bf16_f32 v0, v0, s0
	ds_write_b16 v50, v0 offset:2496
	v_mul_f32_e32 v0, v46, v80
	v_cvt_pk_bf16_f32 v0, v0, s0
	ds_write_b16 v50, v0 offset:3136
	v_mul_f32_e32 v0, v47, v81
	v_cvt_pk_bf16_f32 v0, v0, s0
	ds_write_b16 v50, v0 offset:3264
	v_mul_f32_e32 v0, v48, v82
	v_cvt_pk_bf16_f32 v0, v0, s0
	ds_write_b16 v50, v0 offset:3392
	v_mul_f32_e32 v0, v49, v83
	v_lshrrev_b32_e32 v85, 3, v135
	v_cvt_pk_bf16_f32 v0, v0, s0
	ds_write_b16 v50, v0 offset:3520
	v_or_b32_e32 v0, s94, v85
	v_lshlrev_b32_e32 v0, 13, v0
	v_lshl_add_u64 v[42:43], v[66:67], 0, v[0:1]
	v_or_b32_e32 v0, 8, v85
	v_lshl_add_u32 v87, v85, 7, v86
	s_waitcnt lgkmcnt(0)
	v_lshl_add_u32 v48, v0, 7, v86
	v_or_b32_e32 v0, s94, v0
	ds_read_b128 v[34:37], v87
	v_lshlrev_b32_e32 v0, 13, v0
	ds_read_b128 v[38:41], v48
	v_lshl_add_u64 v[44:45], v[66:67], 0, v[0:1]
	v_or_b32_e32 v0, 16, v85
	v_lshl_add_u32 v49, v0, 7, v86
	v_or_b32_e32 v0, s94, v0
	v_lshlrev_b32_e32 v0, 13, v0
	v_lshl_add_u64 v[46:47], v[66:67], 0, v[0:1]
	v_or_b32_e32 v0, 24, v85
	s_waitcnt lgkmcnt(0)
	global_store_dwordx4 v[42:43], v[34:37], off
	ds_read_b128 v[34:37], v49
	v_lshl_add_u32 v51, v0, 7, v86
	global_store_dwordx4 v[44:45], v[38:41], off
	ds_read_b128 v[38:41], v51
	v_or_b32_e32 v0, s94, v0
	v_lshlrev_b32_e32 v0, 13, v0
	s_waitcnt lgkmcnt(0)
	global_store_dwordx4 v[46:47], v[34:37], off
	s_add_i32 s33, s33, 1
	s_nop 0
	v_lshl_add_u64 v[34:35], v[66:67], 0, v[0:1]
	v_mul_f32_e32 v0, v18, v68
	global_store_dwordx4 v[34:35], v[38:41], off
	v_cvt_pk_bf16_f32 v0, v0, s0
	s_waitcnt lgkmcnt(0)
; #define LAS __attribute__((address_space(3)))
; __device__ __forceinline__ unsigned pk2(float lo, float hi) { f32x2 v = {lo, hi}; bf16x2_t b = __builtin_convertvector(v, bf16x2_t); return __builtin_bit_cast(unsigned, b); }
; #define AB_BAR() asm volatile("s_waitcnt vmcnt(0) lgkmcnt(0)\n\ts_barrier" ::: "memory")
; __device__ __forceinline__ void attn_b_unit(LAS unsigned char* lds, const bf16_t* __restrict__ Q, const bf16_t* __restrict__ K, const bf16_t* __restrict__ V, bf16_t* __restrict__ O, int q0) {
;     ...
;                 stg[orow * 64 + d2 * 32 + r32] = (bf16_t)(pk2(v, 0.f) & 0xffffu); }
;         asm volatile("s_waitcnt lgkmcnt(0)" ::: "memory");
; #pragma unroll
;         for (int i = 0; i < 4; ++i) { const int row = i * 8 + (lane >> 3), ch = lane & 7;
;             const u32x4 v = *(const LAS u32x4*)(stg + row * 64 + ch * 8);
;             *(u32x4*)(O + (size_t)(qw + row) * 4096 + g * 128 + hf * 64 + ch * 8) = v; }
;         asm volatile("s_waitcnt lgkmcnt(0)" ::: "memory");
;     }
;     AB_BAR();
; __device__ __forceinline__ void attn_phase(LAS unsigned char* lds, unsigned char* ws, int l) {
;     ...
;             for (int cmb = 0; cmb < 4; ++cmb) { const int mp = cmb >> 1, sub = cmb & 1;
;                 attn_b_unit(lds, P + P_QB + (size_t)((b * 8 + h) * 2 + mp) * SEQ * 128, P + P_KB + (size_t)((b * 8 + h) * 2 + mp) * SEQ * 128, P + P_VB + (size_t)((b * 8 + h) * 2) * SEQ * 128,
;                             O12 + (size_t)b * SEQ * 4096 + mp * 2048 + h * 256, (qblk * 2 + sub) * 128); }
	ds_write_b16 v50, v0
	v_mul_f32_e32 v0, v19, v69
	v_cvt_pk_bf16_f32 v0, v0, s0
	ds_write_b16 v50, v0 offset:128
	v_mul_f32_e32 v0, v20, v70
	v_cvt_pk_bf16_f32 v0, v0, s0
	ds_write_b16 v50, v0 offset:256
	v_mul_f32_e32 v0, v21, v71
	v_cvt_pk_bf16_f32 v0, v0, s0
	ds_write_b16 v50, v0 offset:384
	v_mul_f32_e32 v0, v22, v72
	v_cvt_pk_bf16_f32 v0, v0, s0
	ds_write_b16 v50, v0 offset:1024
	v_mul_f32_e32 v0, v23, v73
	v_cvt_pk_bf16_f32 v0, v0, s0
	ds_write_b16 v50, v0 offset:1152
	v_mul_f32_e32 v0, v24, v74
	v_cvt_pk_bf16_f32 v0, v0, s0
	ds_write_b16 v50, v0 offset:1280
	v_mul_f32_e32 v0, v25, v75
	v_cvt_pk_bf16_f32 v0, v0, s0
	ds_write_b16 v50, v0 offset:1408
	v_mul_f32_e32 v0, v26, v76
	v_cvt_pk_bf16_f32 v0, v0, s0
	ds_write_b16 v50, v0 offset:2048
	v_mul_f32_e32 v0, v27, v77
	v_cvt_pk_bf16_f32 v0, v0, s0
	ds_write_b16 v50, v0 offset:2176
	v_mul_f32_e32 v0, v28, v78
	v_cvt_pk_bf16_f32 v0, v0, s0
	ds_write_b16 v50, v0 offset:2304
	v_mul_f32_e32 v0, v29, v79
	v_cvt_pk_bf16_f32 v0, v0, s0
	ds_write_b16 v50, v0 offset:2432
	v_mul_f32_e32 v0, v30, v80
	v_cvt_pk_bf16_f32 v0, v0, s0
	ds_write_b16 v50, v0 offset:3072
	v_mul_f32_e32 v0, v31, v81
	v_cvt_pk_bf16_f32 v0, v0, s0
	ds_write_b16 v50, v0 offset:3200
	v_mul_f32_e32 v0, v32, v82
	v_cvt_pk_bf16_f32 v0, v0, s0
	ds_write_b16 v50, v0 offset:3328
	v_mul_f32_e32 v0, v33, v83
	v_cvt_pk_bf16_f32 v0, v0, s0
	ds_write_b16 v50, v0 offset:3456
	v_mul_f32_e32 v0, v2, v68
	v_cvt_pk_bf16_f32 v0, v0, s0
	ds_write_b16 v50, v0 offset:64
	v_mul_f32_e32 v0, v3, v69
	v_cvt_pk_bf16_f32 v0, v0, s0
	ds_write_b16 v50, v0 offset:192
	v_mul_f32_e32 v0, v4, v70
	v_cvt_pk_bf16_f32 v0, v0, s0
	ds_write_b16 v50, v0 offset:320
	v_mul_f32_e32 v0, v5, v71
	v_cvt_pk_bf16_f32 v0, v0, s0
	ds_write_b16 v50, v0 offset:448
	v_mul_f32_e32 v0, v6, v72
	v_cvt_pk_bf16_f32 v0, v0, s0
	ds_write_b16 v50, v0 offset:1088
	v_mul_f32_e32 v0, v7, v73
	v_cvt_pk_bf16_f32 v0, v0, s0
	ds_write_b16 v50, v0 offset:1216
	v_mul_f32_e32 v0, v8, v74
	v_cvt_pk_bf16_f32 v0, v0, s0
	ds_write_b16 v50, v0 offset:1344
	v_mul_f32_e32 v0, v9, v75
	v_cvt_pk_bf16_f32 v0, v0, s0
	ds_write_b16 v50, v0 offset:1472
	v_mul_f32_e32 v0, v10, v76
	v_cvt_pk_bf16_f32 v0, v0, s0
	ds_write_b16 v50, v0 offset:2112
	v_mul_f32_e32 v0, v11, v77
	v_cvt_pk_bf16_f32 v0, v0, s0
	ds_write_b16 v50, v0 offset:2240
	v_mul_f32_e32 v0, v12, v78
	v_cvt_pk_bf16_f32 v0, v0, s0
	ds_write_b16 v50, v0 offset:2368
	v_mul_f32_e32 v0, v13, v79
	v_cvt_pk_bf16_f32 v0, v0, s0
	ds_write_b16 v50, v0 offset:2496
	v_mul_f32_e32 v0, v14, v80
	v_cvt_pk_bf16_f32 v0, v0, s0
	ds_write_b16 v50, v0 offset:3136
	v_mul_f32_e32 v0, v15, v81
	v_cvt_pk_bf16_f32 v0, v0, s0
	ds_write_b16 v50, v0 offset:3264
	v_mul_f32_e32 v0, v16, v82
	v_cvt_pk_bf16_f32 v0, v0, s0
	ds_write_b16 v50, v0 offset:3392
	v_mul_f32_e32 v0, v17, v83
	v_cvt_pk_bf16_f32 v0, v0, s0
	ds_write_b16 v50, v0 offset:3520
	s_waitcnt lgkmcnt(0)
	ds_read_b128 v[2:5], v87
	ds_read_b128 v[6:9], v48
	ds_read_b128 v[10:13], v49
	ds_read_b128 v[14:17], v51
	s_waitcnt lgkmcnt(0)
	global_store_dwordx4 v[42:43], v[2:5], off offset:128
	global_store_dwordx4 v[44:45], v[6:9], off offset:128
	global_store_dwordx4 v[46:47], v[10:13], off offset:128
	global_store_dwordx4 v[34:35], v[14:17], off offset:128
	s_waitcnt lgkmcnt(0)
	s_waitcnt vmcnt(0) lgkmcnt(0)
	s_barrier
	s_xor_b64 s[0:1], s[0:1], -1
	s_cmp_eq_u32 s33, 2
	s_cbranch_scc1 .LBB0_284
.LBB0_252:
	s_mov_b32 s95, s33
	s_or_b32 s20, s95, s40
	s_ashr_i32 s21, s20, 31
	s_lshl_b64 s[20:21], s[20:21], 20
	s_add_u32 s24, s76, s20
	s_addc_u32 s25, s77, s21
	s_add_u32 s28, s78, s20
	s_addc_u32 s29, s79, s21
	s_lshl_b32 s14, s33, 7
	s_and_b32 s14, s14, 0
	v_mov_b32_e32 v40, v222
	s_or_b32 s21, s14, s47
	s_nop 0
	v_readfirstlane_b32 s14, v40
	s_ashr_i32 s20, s14, 6
	s_and_b32 s96, s20, 3
	s_lshl_b32 s15, s96, 5
	v_and_b32_e32 v133, 31, v40
	s_or_b32 s94, s15, s21
	v_or_b32_e32 v41, s94, v133
	v_bfe_u32 v115, v40, 5, 1
	v_lshlrev_b32_e32 v0, 8, v41
	v_lshl_add_u64 v[2:3], s[24:25], 0, v[0:1]
	v_lshlrev_b32_e32 v0, 4, v115
	v_lshl_add_u64 v[2:3], v[2:3], 0, v[0:1]
	s_lshl_b32 s15, s20, 3
	v_bfe_u32 v35, v40, 4, 2
	global_load_dwordx4 v[82:85], v[2:3], off
	global_load_dwordx4 v[86:89], v[2:3], off offset:32
	global_load_dwordx4 v[90:93], v[2:3], off offset:64
	global_load_dwordx4 v[94:97], v[2:3], off offset:96
	global_load_dwordx4 v[98:101], v[2:3], off offset:128
	global_load_dwordx4 v[102:105], v[2:3], off offset:160
	global_load_dwordx4 v[106:109], v[2:3], off offset:192
	global_load_dwordx4 v[110:113], v[2:3], off offset:224
	v_bitop3_b32 v2, s15, v40, v35 bitop3:0x36
	v_lshlrev_b32_e32 v2, 4, v2
	v_or_b32_e32 v0, s15, v35
	v_and_b32_e32 v34, 0xf0, v2
	v_lshl_or_b32 v2, v0, 8, v34
	v_or_b32_e32 v3, 4, v0
	v_bitop3_b32 v0, v0, v40, 4 bitop3:0x36
	v_lshlrev_b32_e32 v0, 4, v0
	v_and_b32_e32 v36, 0xf0, v0
	v_or_b32_e32 v4, s15, v115
	v_lshlrev_b32_e32 v0, 15, v40
	s_lshl_b32 s24, s20, 11
	s_ashr_i32 s72, s14, 8
	v_and_b32_e32 v0, 0x80000, v0
	v_lshlrev_b32_e32 v134, 3, v40
	v_lshlrev_b32_e32 v5, 7, v4
	s_add_i32 s73, s24, 0
	s_lshl_b32 s14, s20, 12
	v_add_u32_e32 v6, v5, v0
	v_and_b32_e32 v7, 32, v40
	v_and_b32_e32 v8, 0x78, v134
	s_mov_b32 m0, s73
	s_add_i32 s97, s14, 0
	v_lshl_or_b32 v3, v3, 8, v36
	v_bitop3_b32 v37, v134, v7, s86 bitop3:0x6c
	v_bitop3_b32 v6, v6, v8, v7 bitop3:0xf6
	v_or_b32_e32 v7, 2, v4
	global_load_lds_dwordx4 v2, s[28:29]
	s_add_i32 m0, s73, 0x400
	s_add_i32 s14, s97, 0x8000
	s_lshl_b32 s26, s72, 5
	v_lshl_add_u32 v8, v7, 7, v0
	v_lshlrev_b32_e32 v7, 5, v7
	global_load_lds_dwordx4 v3, s[28:29]
	s_add_u32 s28, s28, 0x4000
	v_bitop3_b32 v39, v7, s86, v134 bitop3:0x48
	s_waitcnt vmcnt(0) lgkmcnt(0)
	s_barrier
; #define LAS __attribute__((address_space(3)))
; __device__ __forceinline__ void attn_b_unit(LAS unsigned char* lds, const bf16_t* __restrict__ Q, const bf16_t* __restrict__ K, const bf16_t* __restrict__ V, bf16_t* __restrict__ O, int q0) {
;     ...
;     for (int s = 0; s <= NT; ++s) {
;         if (s + 1 < NT) AB_DMAK(s + 1, (s + 1) & 1);
;         if (s < NT) AB_DMAV(s, s & 1);
;         const bool pv_on = (s >= 1) && (64 * (s - 1) <= qw + 31);
;         float hmA = 0.f, hmB = 0.f;
;         if (pv_on) {
;             const int pb = (s - 1) & 1;
;             const LAS float* hm = (const LAS float*)(lds + XOFF + (rg * 2 + pb) * 320);
;             hmA = hm[r32]; hmB = hm[32 + r32];
;             const LAS unsigned char* pp = lds + POFF + (rg * 2 + pb) * 4096 + lane * 16;
;             bf16x8 pa[4];
; #pragma unroll
;             for (int s2 = 0; s2 < 4; ++s2) pa[s2] = *(const LAS bf16x8*)(pp + s2 * 1024);
;             const LAS unsigned char* vp = lds + VOFF + pb * VBB + vlane;
;             s16x4 vlo[4][4], vhi[4][4];
; #pragma unroll
;             for (int s2 = 0; s2 < 4; ++s2)
; #pragma unroll
;                 for (int db = 0; db < 4; ++db) {
;                     vlo[s2][db] = __builtin_bit_cast(s16x4, __builtin_amdgcn_ds_read_tr16_b64_v4i16((LAS s16x4*)(vp + vdb[db] + s2 * 16 * VSTR)));
;                     vhi[s2][db] = __builtin_bit_cast(s16x4, __builtin_amdgcn_ds_read_tr16_b64_v4i16((LAS s16x4*)(vp + vdb[db] + s2 * 16 * VSTR + 8 * VSTR))); }
;             __builtin_amdgcn_sched_barrier(0);
;             lrun += pend; pend = 0.f;
; #pragma unroll
;             for (int s2 = 0; s2 < 4; ++s2)
; #pragma unroll
;                 for (int db = 0; db < 4; ++db) {
;                     const s16x4 lo = vlo[s2][db], hi4 = vhi[s2][db];
;                     const bf16x8 vf = (bf16x8){lo[0], lo[1], lo[2], lo[3], hi4[0], hi4[1], hi4[2], hi4[3]};
;                     o[db] = __builtin_amdgcn_mfma_f32_32x32x16_bf16(pa[s2], vf, o[db], 0, 0, 0); }
;             const float mxa = fmaxf(hmA, hmB);
;             const bool grow = mxa > mrun + 8.0f;
;             if (__any(grow)) {
;                 const float mn = grow ? mxa : mrun;
;                 const float f = __builtin_amdgcn_exp2f(mrun - mn);
;                 mrun = mn; lrun *= f;
;                 LAS float* wsf = (LAS float*)(lds + WOFF + wid * 128);
;                 if (hi == 0) wsf[r32] = f;
	s_addc_u32 s29, s29, 0
	s_add_i32 m0, s73, 0x4000
	v_or_b32_e32 v7, v39, v8
	v_or_b32_e32 v8, v0, v37
	v_or_b32_e32 v4, 6, v4
	global_load_lds_dwordx4 v2, s[28:29]
	s_add_i32 m0, s73, 0x4400
	v_lshlrev_b32_e32 v6, 1, v6
	v_add_u32_e32 v5, v5, v8
	v_lshl_add_u32 v8, v4, 7, v0
	v_lshlrev_b32_e32 v4, 5, v4
	global_load_lds_dwordx4 v3, s[28:29]
	s_mov_b32 m0, s14
	v_lshlrev_b32_e32 v7, 1, v7
	v_bitop3_b32 v38, v4, s86, v134 bitop3:0x48
	global_load_lds_dwordx4 v6, s[42:43]
	s_add_i32 m0, s97, 0x8400
	v_lshl_or_b32 v5, v5, 1, v232
	v_or_b32_e32 v4, v38, v8
	global_load_lds_dwordx4 v7, s[42:43]
	s_add_i32 m0, s97, 0x8800
	v_lshlrev_b32_e32 v4, 1, v4
	global_load_lds_dwordx4 v5, s[42:43]
	s_add_i32 m0, s97, 0x8c00
	v_bitop3_b32 v2, v115, v40, 15 bitop3:0x78
	global_load_lds_dwordx4 v4, s[42:43]
	v_or_b32_e32 v43, s26, v133
	v_lshlrev_b32_e32 v138, 4, v2
	v_lshl_add_u32 v139, v43, 8, 0
	v_xor_b32_e32 v140, 32, v138
	v_add_u32_e32 v2, v139, v138
	v_add_u32_e32 v6, v139, v140
	v_xor_b32_e32 v141, 64, v138
	ds_read_b128 v[2:5], v2
	ds_read_b128 v[18:21], v6
	v_add_u32_e32 v6, v139, v141
	v_xor_b32_e32 v142, 0x60, v138
	v_xor_b32_e32 v143, 0x80, v138
	v_add_u32_e32 v7, v139, v142
	ds_read_b128 v[22:25], v6
	ds_read_b128 v[26:29], v7
	v_add_u32_e32 v6, v139, v143
	v_xor_b32_e32 v144, 0xa0, v138
	v_xor_b32_e32 v145, 0xc0, v138
	v_add_u32_e32 v7, v139, v144
	ds_read_b128 v[30:33], v6
	ds_read_b128 v[44:47], v7
	v_add_u32_e32 v6, v139, v145
	v_xor_b32_e32 v146, 0xe0, v138
	v_add_u32_e32 v7, v139, v146
	ds_read_b128 v[48:51], v6
	ds_read_b128 v[52:55], v7
	v_lshlrev_b32_e32 v42, 2, v115
	v_sub_u32_e32 v147, v41, v42
	s_waitcnt vmcnt(0) lgkmcnt(0)
	v_mfma_f32_32x32x16_bf16 v[2:17], v[2:5], v[82:85], 0
	s_cmp_gt_u32 s94, 62
	v_mfma_f32_32x32x16_bf16 v[2:17], v[18:21], v[86:89], v[2:17]
	v_mfma_f32_32x32x16_bf16 v[2:17], v[22:25], v[90:93], v[2:17]
	v_mfma_f32_32x32x16_bf16 v[2:17], v[26:29], v[94:97], v[2:17]
	v_mfma_f32_32x32x16_bf16 v[2:17], v[30:33], v[98:101], v[2:17]
	v_mfma_f32_32x32x16_bf16 v[2:17], v[44:47], v[102:105], v[2:17]
	v_mfma_f32_32x32x16_bf16 v[2:17], v[48:51], v[106:109], v[2:17]
	v_mfma_f32_32x32x16_bf16 v[2:17], v[52:55], v[110:113], v[2:17]
	s_cbranch_scc1 .LBB0_254
	v_cmp_le_i32_e32 vcc, s26, v147
	s_or_b32 s14, s26, 2
	s_nop 8
	v_cndmask_b32_e32 v2, v229, v2, vcc
	v_cmp_lt_i32_e32 vcc, s26, v147
	s_nop 1
	v_cndmask_b32_e32 v3, v229, v3, vcc
	v_cmp_le_i32_e32 vcc, s14, v147
	s_or_b32 s14, s26, 3
	s_nop 0
	v_cndmask_b32_e32 v4, v229, v4, vcc
	v_cmp_le_i32_e32 vcc, s14, v147
	s_or_b32 s14, s26, 8
	s_nop 0
	v_cndmask_b32_e32 v5, v229, v5, vcc
	v_cmp_le_i32_e32 vcc, s14, v147
	s_or_b32 s14, s26, 9
	s_nop 0
	v_cndmask_b32_e32 v6, v229, v6, vcc
	v_cmp_le_i32_e32 vcc, s14, v147
	s_or_b32 s14, s26, 10
	s_nop 0
	v_cndmask_b32_e32 v7, v229, v7, vcc
	v_cmp_le_i32_e32 vcc, s14, v147
	s_or_b32 s14, s26, 11
	s_nop 0
	v_cndmask_b32_e32 v8, v229, v8, vcc
	v_cmp_le_i32_e32 vcc, s14, v147
	s_or_b32 s14, s26, 16
	s_nop 0
	v_cndmask_b32_e32 v9, v229, v9, vcc
	v_cmp_le_i32_e32 vcc, s14, v147
	s_or_b32 s14, s26, 17
	s_nop 0
	v_cndmask_b32_e32 v10, v229, v10, vcc
	v_cmp_le_i32_e32 vcc, s14, v147
	s_or_b32 s14, s26, 18
	s_nop 0
	v_cndmask_b32_e32 v11, v229, v11, vcc
	v_cmp_le_i32_e32 vcc, s14, v147
	s_or_b32 s14, s26, 19
	s_nop 0
	v_cndmask_b32_e32 v12, v229, v12, vcc
	v_cmp_le_i32_e32 vcc, s14, v147
	s_or_b32 s14, s26, 24
	s_nop 0
	v_cndmask_b32_e32 v13, v229, v13, vcc
	v_cmp_le_i32_e32 vcc, s14, v147
	s_or_b32 s14, s26, 25
	s_nop 0
	v_cndmask_b32_e32 v14, v229, v14, vcc
	v_cmp_le_i32_e32 vcc, s14, v147
	s_or_b32 s14, s26, 26
	s_nop 0
	v_cndmask_b32_e32 v15, v229, v15, vcc
	v_cmp_le_i32_e32 vcc, s14, v147
	s_or_b32 s14, s26, 27
	s_nop 0
	v_cndmask_b32_e32 v16, v229, v16, vcc
	v_cmp_le_i32_e32 vcc, s14, v147
	s_nop 1
	v_cndmask_b32_e32 v17, v229, v17, vcc
.LBB0_254:
	v_bitop3_b32 v18, s26, v133, 32 bitop3:0xde
	v_lshl_add_u32 v52, v18, 8, 0
	v_add_u32_e32 v18, v52, v138
	ds_read_b128 v[18:21], v18
	v_add_u32_e32 v22, v52, v140
	ds_read_b128 v[44:47], v22
	v_add_u32_e32 v48, v52, v141
	s_nop 3
	v_max_f32_e32 v53, v3, v3
	v_max_f32_e32 v54, v2, v2
	v_max_f32_e32 v53, v54, v53
	v_and_b32_e32 v56, 64, v230
	v_xor_b32_e32 v55, 32, v230
	s_waitcnt lgkmcnt(1)
	v_mfma_f32_32x32x16_bf16 v[18:33], v[18:21], v[82:85], 0
	v_add_u32_e32 v132, 64, v56
	v_bitop3_b32 v57, s26, v42, 32 bitop3:0xde
	v_cmp_lt_i32_e32 vcc, v55, v132
	v_or_b32_e32 v54, 2, v57
	v_or_b32_e32 v56, 3, v57
	v_or_b32_e32 v58, 8, v57
	v_or_b32_e32 v59, 9, v57
	s_waitcnt lgkmcnt(0)
	v_mfma_f32_32x32x16_bf16 v[18:33], v[44:47], v[86:89], v[18:33]
	ds_read_b128 v[44:47], v48
	v_add_u32_e32 v48, v52, v142
	ds_read_b128 v[48:51], v48
	v_or_b32_e32 v60, 10, v57
	v_or_b32_e32 v61, 11, v57
	v_or_b32_e32 v62, 16, v57
	v_or_b32_e32 v63, 17, v57
	v_or_b32_e32 v64, 18, v57
	s_waitcnt lgkmcnt(1)
	v_mfma_f32_32x32x16_bf16 v[18:33], v[44:47], v[90:93], v[18:33]
	v_add_u32_e32 v44, v52, v143
	ds_read_b128 v[44:47], v44
	v_and_b32_e32 v135, 63, v40
	v_cmp_lt_u32_e64 s[36:37], 31, v135
	v_cmp_gt_u32_e64 s[38:39], 32, v135
	v_lshl_add_u32 v149, v43, 2, s87
	s_waitcnt lgkmcnt(1)
	v_mfma_f32_32x32x16_bf16 v[18:33], v[48:51], v[94:97], v[18:33]
	v_add_u32_e32 v48, v52, v144
	ds_read_b128 v[48:51], v48
	s_waitcnt lgkmcnt(1)
	v_mfma_f32_32x32x16_bf16 v[18:33], v[44:47], v[98:101], v[18:33]
	v_add_u32_e32 v44, v52, v145
	ds_read_b128 v[44:47], v44
	s_waitcnt lgkmcnt(1)
	v_mfma_f32_32x32x16_bf16 v[18:33], v[48:51], v[102:105], v[18:33]
	v_max3_f32 v48, v53, v4, v5
	v_add_u32_e32 v49, v52, v146
	v_max3_f32 v52, v48, v6, v7
	ds_read_b128 v[48:51], v49
	v_cndmask_b32_e32 v53, v230, v55, vcc
	v_cmp_lt_i32_e32 vcc, v57, v41
	v_lshlrev_b32_e32 v131, 2, v53
	s_waitcnt lgkmcnt(1)
; #define LAS __attribute__((address_space(3)))
; __device__ __forceinline__ unsigned pk2(float lo, float hi) { f32x2 v = {lo, hi}; bf16x2_t b = __builtin_convertvector(v, bf16x2_t); return __builtin_bit_cast(unsigned, b); }
; __device__ __forceinline__ void attn_b_unit(LAS unsigned char* lds, const bf16_t* __restrict__ Q, const bf16_t* __restrict__ K, const bf16_t* __restrict__ V, bf16_t* __restrict__ O, int q0) {
;     ...
;             float mx = sh[0];
; #pragma unroll
;             for (int r = 1; r < 16; ++r) mx = fmaxf(mx, sh[r]);
;             mx = fmaxf(mx, __shfl_xor(mx, 32));
;             if (s == 0) {
;                 const LAS unsigned char* kq = lds + pb * KBB + (32 * (g ^ 1) + r32) * KSTR;
;                 f32x16 so;
; #pragma unroll
;                 for (int r = 0; r < 16; ++r) so[r] = 0.f;
; #pragma unroll
;                 for (int ks = 0; ks < 8; ++ks) { const bf16x8 kf = *(const LAS bf16x8*)(kq + ((kc0 ^ (2 * ks)) << 4)); so = __builtin_amdgcn_mfma_f32_32x32x16_bf16(kf, qf[ks], so, 0, 0, 0); }
;                 float mo = -3.0e38f;
; #pragma unroll
;                 for (int r = 0; r < 16; ++r) { const int kv = 32 * (g ^ 1) + (r & 3) + 8 * (r >> 2) + 4 * hi; mo = fmaxf(mo, (kv <= q) ? so[r] : -3.0e38f); }
;                 mo = fmaxf(mo, __shfl_xor(mo, 32));
;                 mrun = fmaxf(mx, mo);
;             }
;             LAS float* hm = (LAS float*)(lds + XOFF + (rg * 2 + pb) * 320);
;             if (hi == 0) hm[32 * g + r32] = mx;
;             float ps0 = 0.f, ps1 = 0.f;
;             LAS unsigned char* pp = lds + POFF + (rg * 2 + pb) * 4096 + lane * 16 + g * 2048;
; #pragma unroll
;             for (int sp = 0; sp < 2; ++sp) {
;                 float p[8];
; #pragma unroll
;                 for (int j = 0; j < 8; ++j) p[j] = __builtin_amdgcn_exp2f(sh[8 * sp + j] - mrun);
;                 ps0 += (p[0] + p[1]) + (p[2] + p[3]); ps1 += (p[4] + p[5]) + (p[6] + p[7]);
;                 u32x4 pw; pw.x = pk2(p[0], p[1]); pw.y = pk2(p[2], p[3]); pw.z = pk2(p[4], p[5]); pw.w = pk2(p[6], p[7]);
;                 *(LAS u32x4*)(pp + sp * 1024) = pw;
;             }
;             pend = ps0 + ps1;
	v_mfma_f32_32x32x16_bf16 v[18:33], v[44:47], v[106:109], v[18:33]
	v_max3_f32 v44, v52, v8, v9
	v_max3_f32 v44, v44, v10, v11
	v_max3_f32 v44, v44, v12, v13
	v_max3_f32 v44, v44, v14, v15
	v_max3_f32 v44, v44, v16, v17
	ds_bpermute_b32 v45, v131, v44
	s_waitcnt lgkmcnt(1)
	v_mfma_f32_32x32x16_bf16 v[18:33], v[48:51], v[110:113], v[18:33]
	s_nop 11
	v_cndmask_b32_e32 v19, v229, v19, vcc
	v_cmp_le_i32_e32 vcc, v54, v41
	v_max_f32_e32 v18, v18, v18
	v_max_f32_e32 v18, 0xff61b1e6, v18
	v_cndmask_b32_e32 v20, v229, v20, vcc
	v_cmp_le_i32_e32 vcc, v56, v41
	v_max_f32_e32 v19, v19, v19
	s_nop 0
	v_cndmask_b32_e32 v21, v229, v21, vcc
	v_cmp_le_i32_e32 vcc, v58, v41
	s_nop 1
	v_cndmask_b32_e32 v22, v229, v22, vcc
	v_cmp_le_i32_e32 vcc, v59, v41
	s_nop 1
	v_cndmask_b32_e32 v23, v229, v23, vcc
	v_cmp_le_i32_e32 vcc, v60, v41
	s_nop 1
	v_cndmask_b32_e32 v24, v229, v24, vcc
	v_cmp_le_i32_e32 vcc, v61, v41
	s_nop 1
	v_cndmask_b32_e32 v25, v229, v25, vcc
	v_cmp_le_i32_e32 vcc, v62, v41
	s_nop 1
	v_cndmask_b32_e32 v26, v229, v26, vcc
	v_cmp_le_i32_e32 vcc, v63, v41
	s_nop 1
	v_cndmask_b32_e32 v27, v229, v27, vcc
	v_cmp_le_i32_e32 vcc, v57, v41
	s_nop 1
	v_cndmask_b32_e32 v18, v229, v18, vcc
	v_max_f32_e32 v18, v18, v19
	v_max3_f32 v18, v18, v20, v21
	v_max3_f32 v18, v18, v22, v23
	v_cmp_le_i32_e32 vcc, v64, v41
	v_or_b32_e32 v20, 19, v57
	v_max3_f32 v18, v18, v24, v25
	v_cndmask_b32_e32 v19, v229, v28, vcc
	v_cmp_le_i32_e32 vcc, v20, v41
	v_max3_f32 v18, v18, v26, v27
	s_nop 0
	v_cndmask_b32_e32 v20, v229, v29, vcc
	v_max3_f32 v18, v18, v19, v20
	v_or_b32_e32 v19, 24, v57
	v_cmp_le_i32_e32 vcc, v19, v41
	v_or_b32_e32 v20, 25, v57
	s_nop 0
	v_cndmask_b32_e32 v19, v229, v30, vcc
	v_cmp_le_i32_e32 vcc, v20, v41
	s_nop 1
	v_cndmask_b32_e32 v20, v229, v31, vcc
	v_max3_f32 v18, v18, v19, v20
	v_or_b32_e32 v19, 26, v57
	v_cmp_le_i32_e32 vcc, v19, v41
	v_or_b32_e32 v20, 27, v57
	s_nop 0
	v_cndmask_b32_e32 v19, v229, v32, vcc
	v_cmp_le_i32_e32 vcc, v20, v41
	s_nop 1
	v_cndmask_b32_e32 v20, v229, v33, vcc
	v_max3_f32 v18, v18, v19, v20
	ds_bpermute_b32 v19, v131, v18
	s_waitcnt lgkmcnt(1)
	v_max_f32_e32 v20, v45, v45
	v_max_f32_e32 v20, v44, v20
	s_and_saveexec_b64 s[70:71], s[38:39]
	s_mul_i32 s14, s96, 0x280
	v_add_u32_e32 v21, s14, v149
	ds_write_b32 v21, v20
	s_or_b64 exec, exec, s[70:71]
	s_waitcnt lgkmcnt(0)
	v_max3_f32 v67, v20, v18, v19
	v_cndmask_b32_e64 v18, 0, 1, s[0:1]
	v_lshrrev_b32_e32 v20, 3, v40
	v_readfirstlane_b32 s14, v18
	s_mov_b32 s14, 0
	s_add_i32 s14, s13, s14
	s_lshl_b32 s14, s14, 8
	s_and_b32 s14, s14, 0x3fc000
	s_add_u32 s48, s14, 0xffffc000
	v_bfe_u32 v18, v40, 2, 2
	s_lshl_b32 s14, s72, 4
	v_and_b32_e32 v20, 2, v20
	v_bfe_u32 v21, v40, 1, 1
	v_or_b32_e32 v19, v42, v18
	v_or3_b32 v20, s14, v20, v21
	v_lshlrev_b32_e32 v153, 6, v18
	v_lshlrev_b32_e32 v18, 4, v20
	v_and_b32_e32 v20, 8, v134
	v_lshl_add_u32 v19, v19, 9, 0
	v_sub_f32_e32 v2, v2, v67
	v_add3_u32 v154, v19, v18, v20
	v_exp_f32_e32 v18, v2
	v_sub_f32_e32 v2, v3, v67
	s_add_i32 s14, 0, 0x18000
	v_exp_f32_e32 v20, v2
	v_sub_f32_e32 v2, v4, v67
	v_lshl_add_u32 v156, v135, 4, s14
	s_lshl_b32 s14, s20, 7
	v_exp_f32_e32 v22, v2
	v_sub_f32_e32 v2, v5, v67
	s_add_i32 s14, s14, 0
	v_exp_f32_e32 v24, v2
	v_sub_f32_e32 v2, v6, v67
	v_lshlrev_b32_e32 v21, 2, v133
	s_add_i32 s14, s14, 0x20e00
	v_exp_f32_e32 v19, v2
	v_sub_f32_e32 v2, v7, v67
	v_add_u32_e32 v155, s87, v21
	v_add_u32_e32 v137, s14, v21
	v_exp_f32_e32 v21, v2
	v_sub_f32_e32 v2, v8, v67
	v_exp_f32_e32 v23, v2
	v_sub_f32_e32 v2, v9, v67
	v_exp_f32_e32 v25, v2
	v_lshl_add_u32 v157, s72, 11, v156
	v_lshl_add_u32 v26, s96, 13, v157
	v_cvt_pk_bf16_f32 v2, v18, v20
	v_cvt_pk_bf16_f32 v3, v22, v24
	v_cvt_pk_bf16_f32 v4, v19, v21
	v_cvt_pk_bf16_f32 v5, v23, v25
	ds_write_b128 v26, v[2:5]
	v_sub_f32_e32 v2, v10, v67
	v_exp_f32_e32 v4, v2
	v_sub_f32_e32 v2, v11, v67
	v_exp_f32_e32 v6, v2
	v_sub_f32_e32 v2, v12, v67
	v_exp_f32_e32 v8, v2
	v_sub_f32_e32 v2, v13, v67
	v_exp_f32_e32 v10, v2
	v_sub_f32_e32 v2, v14, v67
	v_exp_f32_e32 v5, v2
	v_sub_f32_e32 v2, v15, v67
	v_exp_f32_e32 v7, v2
	v_sub_f32_e32 v2, v16, v67
	v_exp_f32_e32 v9, v2
	v_sub_f32_e32 v2, v17, v67
	v_exp_f32_e32 v11, v2
	v_pk_add_f32 v[2:3], v[18:19], v[20:21]
	v_pk_add_f32 v[12:13], v[22:23], v[24:25]
	s_add_i32 s28, s46, s95
	v_pk_add_f32 v[2:3], v[2:3], v[12:13]
	v_pk_add_f32 v[12:13], v[4:5], v[6:7]
	v_pk_add_f32 v[14:15], v[8:9], v[10:11]
	v_pk_add_f32 v[2:3], v[2:3], 0 op_sel_hi:[1,0]
	v_pk_add_f32 v[12:13], v[12:13], v[14:15]
	s_ashr_i32 s29, s28, 31
	v_pk_add_f32 v[12:13], v[12:13], v[2:3]
	v_cvt_pk_bf16_f32 v2, v4, v6
	v_cvt_pk_bf16_f32 v3, v8, v10
	v_cvt_pk_bf16_f32 v4, v5, v7
	v_cvt_pk_bf16_f32 v5, v9, v11
	ds_write_b128 v26, v[2:5] offset:1024
	v_lshl_add_u32 v2, s20, 10, v0
	v_add_u32_e32 v0, v2, v37
	v_lshlrev_b32_e32 v3, 7, v115
	v_add_lshl_u32 v0, v0, v3, 1
	v_add_u32_e32 v2, v2, v3
	v_lshl_add_u64 v[118:119], s[58:59], 0, v[0:1]
	v_add_u32_e32 v0, v2, v39
	v_lshl_add_u32 v0, v0, 1, v233
	v_lshl_add_u64 v[120:121], s[58:59], 0, v[0:1]
	v_add_u32_e32 v0, v2, v37
	s_addk_i32 s21, 0x80
	v_lshl_add_u32 v0, v0, 1, v232
	s_lshl_b64 s[70:71], s[28:29], 20
	s_lshr_b32 s28, s21, 6
	s_or_b32 s49, s94, 31
	s_lshl_b32 s29, s96, 1
	v_lshl_add_u32 v136, v42, 2, s14
	v_lshl_add_u64 v[122:123], s[58:59], 0, v[0:1]
	v_add_u32_e32 v0, v2, v38
	s_add_i32 s14, s24, 0x400
	v_lshl_add_u32 v0, v0, 1, v234
	v_lshlrev_b32_e32 v2, 8, v35
	s_add_u32 s70, s80, s70
	v_lshl_add_u64 v[124:125], s[58:59], 0, v[0:1]
	v_add3_u32 v0, s14, v2, v36
	s_addc_u32 s71, s81, s71
	v_lshl_add_u64 v[126:127], s[70:71], 0, v[0:1]
	v_add3_u32 v0, s24, v2, v34
	v_mov_b32_e32 v14, v1
	v_mov_b32_e32 v15, v1
	v_add_f32_e32 v66, v12, v13
	s_waitcnt vmcnt(0) lgkmcnt(0)
	s_barrier
; #define AB_DMAK(t, b) do { const char* _gb = (const char*)K + (size_t)(64 * (t)) * 128 * 2; _Pragma("unroll") for (int _j = 0; _j < 2; ++_j) \
;         __builtin_amdgcn_global_load_lds((const unsigned*)(_gb + kgoff[_j]), (LAS unsigned*)(lds + (b) * KBB + (2 * wid + _j) * 1024), 16, 0, 0); } while (0)
; #define AB_DMAV(t, b) do { const char* _gb = (const char*)V + (size_t)(64 * (t)) * 128 * 2; _Pragma("unroll") for (int _j = 0; _j < 4; ++_j) \
;         __builtin_amdgcn_global_load_lds((const unsigned*)(_gb + vgoff[_j]), (LAS unsigned*)(lds + VOFF + (b) * VBB + (4 * wid + _j) * 1024), 16, 0, 0); } while (0)
; __device__ __forceinline__ void attn_b_unit(LAS unsigned char* lds, const bf16_t* __restrict__ Q, const bf16_t* __restrict__ K, const bf16_t* __restrict__ V, bf16_t* __restrict__ O, int q0) {
;     ...
;     f32x16 o[4];
; #pragma unroll
;     for (int db = 0; db < 4; ++db)
; #pragma unroll
;         for (int r = 0; r < 16; ++r) o[db][r] = 0.f;
;     float mrun = -1.0e30f, lrun = 0.f, pend = 0.f;
;     const int NT = (q0 + 128) >> 6;
;     ...
;     for (int s = 0; s <= NT; ++s) {
;         if (s + 1 < NT) AB_DMAK(s + 1, (s + 1) & 1);
;         if (s < NT) AB_DMAV(s, s & 1);
	v_lshl_add_u64 v[128:129], s[70:71], 0, v[0:1]
	v_mov_b32_e32 v0, v1
	v_mov_b32_e32 v2, v1
	v_mov_b32_e32 v3, v1
	v_mov_b32_e32 v4, v1
	v_mov_b32_e32 v5, v1
	v_mov_b32_e32 v6, v1
	v_mov_b32_e32 v7, v1
	v_mov_b32_e32 v8, v1
	v_mov_b32_e32 v9, v1
	v_mov_b32_e32 v10, v1
	v_mov_b32_e32 v11, v1
	v_mov_b32_e32 v12, v1
	v_mov_b32_e32 v13, v1
	v_mov_b64_e32 v[64:65], v[14:15]
	v_mov_b64_e32 v[48:49], v[14:15]
	v_mov_b64_e32 v[32:33], v[14:15]
	v_mov_b64_e32 v[62:63], v[12:13]
	v_mov_b64_e32 v[60:61], v[10:11]
	v_mov_b64_e32 v[58:59], v[8:9]
	v_mov_b64_e32 v[56:57], v[6:7]
	v_mov_b64_e32 v[54:55], v[4:5]
	v_mov_b64_e32 v[52:53], v[2:3]
	v_mov_b64_e32 v[50:51], v[0:1]
	v_mov_b64_e32 v[46:47], v[12:13]
	v_mov_b64_e32 v[44:45], v[10:11]
	v_mov_b64_e32 v[42:43], v[8:9]
	v_mov_b64_e32 v[40:41], v[6:7]
	v_mov_b64_e32 v[38:39], v[4:5]
	v_mov_b64_e32 v[36:37], v[2:3]
	v_mov_b64_e32 v[34:35], v[0:1]
	v_mov_b64_e32 v[30:31], v[12:13]
	v_mov_b64_e32 v[28:29], v[10:11]
	v_mov_b64_e32 v[26:27], v[8:9]
	v_mov_b64_e32 v[24:25], v[6:7]
	v_mov_b64_e32 v[22:23], v[4:5]
	v_mov_b64_e32 v[20:21], v[2:3]
	v_mov_b64_e32 v[18:19], v[0:1]
	v_mov_b64_e32 v[16:17], v[14:15]
	v_xor_b32_e32 v152, 64, v153
	v_xor_b32_e32 v151, 0x80, v153
	v_xor_b32_e32 v150, 0xc0, v153
	s_mov_b32 s21, 1
	v_mov_b32_e32 v148, 0
	s_mov_b64 s[70:71], 0
	s_mov_b32 s24, 0x8000
	s_movk_i32 s25, 0x7f
	v_mov_b64_e32 v[14:15], v[12:13]
	v_mov_b64_e32 v[12:13], v[10:11]
	v_mov_b64_e32 v[10:11], v[8:9]
	v_mov_b64_e32 v[8:9], v[6:7]
	v_mov_b64_e32 v[6:7], v[4:5]
	v_mov_b64_e32 v[4:5], v[2:3]
	v_mov_b64_e32 v[2:3], v[0:1]
	s_add_i32 s20, s21, 1
	s_cmp_ge_u32 s20, s28
	s_cbranch_scc1 .LBB0_258

; #define INP(i) inptr(lds, (i))
; __device__ __forceinline__ void attn_phase(LAS unsigned char* lds, unsigned char* ws, int l) {
;     ...
;             __builtin_amdgcn_fence(__ATOMIC_RELEASE, "workgroup"); __syncthreads(); __builtin_amdgcn_fence(__ATOMIC_ACQUIRE, "workgroup");
;             int tid = threadIdx.x; asm volatile("" : "+v"(tid));
;             const int lane = tid & 63, wv = tid >> 6;
;             const float lam_init = 0.8f - 0.6f * expf(-0.3f * (float)l);
;             const float* q1 = INP(3) + l * 128; const float* k1 = INP(4) + l * 128; const float* q2 = INP(5) + l * 128; const float* k2 = INP(6) + l * 128;
;             const float d1 = wave_sum(q1[lane] * k1[lane] + q1[lane + 64] * k1[lane + 64]), d2 = wave_sum(q2[lane] * k2[lane] + q2[lane + 64] * k2[lane + 64]);
;             const float lam = expf(d1) - expf(d2) + lam_init;
;             const f32x4 g = *(const f32x4*)(INP(7) + l * 256 + 4 * lane) * (1.0f - lam_init);
.LBB0_284:
	v_mov_b32_e32 v20, v222
	v_mov_b32_e32 v0, s88
	s_waitcnt vmcnt(0)
	s_barrier
	ds_read2_b64 v[2:5], v0 offset1:1
	v_mov_b32_e32 v0, s89
	ds_read2_b64 v[6:9], v0 offset1:1
	v_and_b32_e32 v21, 63, v20
	v_lshlrev_b32_e32 v0, 2, v21
	s_waitcnt lgkmcnt(1)
	v_readfirstlane_b32 s0, v2
	v_readfirstlane_b32 s1, v3
	s_add_u32 s0, s0, s6
	s_addc_u32 s1, s1, s7
	v_readfirstlane_b32 s13, v4
	v_readfirstlane_b32 s14, v5
	s_add_u32 s20, s13, s6
	s_addc_u32 s21, s14, s7
	s_waitcnt lgkmcnt(0)
	v_readfirstlane_b32 s13, v6
	v_readfirstlane_b32 s14, v7
	s_add_u32 s24, s13, s6
	v_lshl_add_u64 v[2:3], s[0:1], 0, v[0:1]
	s_addc_u32 s25, s14, s7
	v_readfirstlane_b32 s13, v8
	v_lshl_add_u64 v[4:5], s[20:21], 0, v[0:1]
	flat_load_dword v6, v[2:3]
	flat_load_dword v7, v[2:3] offset:256
	s_nop 0
	flat_load_dword v2, v[4:5]
	flat_load_dword v3, v[4:5] offset:256
	v_readfirstlane_b32 s14, v9
	s_add_u32 s28, s13, s6
	s_addc_u32 s29, s14, s7
	v_lshl_add_u64 v[4:5], s[24:25], 0, v[0:1]
	v_lshl_add_u64 v[8:9], s[28:29], 0, v[0:1]
	flat_load_dword v18, v[4:5]
	flat_load_dword v19, v[4:5] offset:256
	s_nop 0
	flat_load_dword v4, v[8:9]
	flat_load_dword v5, v[8:9] offset:256
	v_mov_b32_e32 v0, s90
	ds_read_b64 v[8:9], v0
	v_lshlrev_b32_e32 v0, 4, v21
	v_xor_b32_e32 v14, 8, v230
	v_xor_b32_e32 v15, 16, v230
	v_mov_b32_e32 v115, v114
	s_waitcnt lgkmcnt(0)
	v_readfirstlane_b32 s0, v8
	v_readfirstlane_b32 s1, v9
	s_add_u32 s0, s0, s30
	s_addc_u32 s1, s1, s31
	v_lshl_add_u64 v[8:9], s[0:1], 0, v[0:1]
	flat_load_dwordx4 v[10:13], v[8:9]
	v_xor_b32_e32 v0, 1, v230
	v_cmp_lt_i32_e32 vcc, v0, v132
	v_xor_b32_e32 v8, 2, v230
	v_xor_b32_e32 v9, 4, v230
	v_cndmask_b32_e32 v0, v230, v0, vcc
	v_lshlrev_b32_e32 v0, 2, v0
	v_cmp_lt_i32_e32 vcc, v8, v132
	s_mov_b32 s1, s35
	s_or_b32 s0, s34, s47
	v_cndmask_b32_e32 v8, v230, v8, vcc
	v_cmp_lt_i32_e32 vcc, v9, v132
	s_mov_b64 s[36:37], 0
	s_waitcnt vmcnt(0)
	v_pk_mul_f32 v[2:3], v[6:7], v[2:3]
	s_nop 0
	v_add_f32_e32 v6, v2, v3
	ds_bpermute_b32 v7, v0, v6
	v_cndmask_b32_e32 v9, v230, v9, vcc
	v_cmp_lt_i32_e32 vcc, v14, v132
	v_pk_mul_f32 v[2:3], v[18:19], v[4:5]
	s_nop 0
	v_add_f32_e32 v4, v2, v3
	ds_bpermute_b32 v5, v0, v4
	v_cndmask_b32_e32 v16, v230, v14, vcc
	v_lshlrev_b32_e32 v14, 2, v8
	v_ashrrev_i32_e32 v8, 2, v20
	s_waitcnt lgkmcnt(0)
	v_add_f32_e32 v6, v6, v7
	v_cmp_lt_i32_e32 vcc, v15, v132
	v_and_b32_e32 v8, 0xfffffff0, v8
	ds_bpermute_b32 v7, v14, v6
	v_cndmask_b32_e32 v17, v230, v15, vcc
	v_lshlrev_b32_e32 v15, 2, v9
	v_ashrrev_i32_e32 v9, 31, v8
	v_lshl_add_u64 v[2:3], s[0:1], 0, v[8:9]
	v_add_f32_e32 v8, v4, v5
	ds_bpermute_b32 v9, v14, v8
	s_waitcnt lgkmcnt(1)
	v_add_f32_e32 v6, v6, v7
	ds_bpermute_b32 v7, v15, v6
	v_lshlrev_b32_e32 v16, 2, v16
	v_lshlrev_b32_e32 v17, 2, v17
	s_waitcnt lgkmcnt(1)
	v_add_f32_e32 v8, v8, v9
	ds_bpermute_b32 v9, v15, v8
	s_waitcnt lgkmcnt(1)
	v_add_f32_e32 v6, v6, v7
	ds_bpermute_b32 v7, v16, v6
	v_lshlrev_b32_e32 v20, 3, v21
	v_lshlrev_b64 v[4:5], 12, v[2:3]
	s_waitcnt lgkmcnt(1)
	v_add_f32_e32 v8, v8, v9
	ds_bpermute_b32 v9, v16, v8
	s_waitcnt lgkmcnt(1)
	v_add_f32_e32 v18, v6, v7
	v_lshlrev_b64 v[2:3], 13, v[2:3]
	ds_bpermute_b32 v19, v17, v18
	v_or_b32_e32 v2, v2, v20
	v_lshl_add_u64 v[6:7], s[8:9], 0, v[2:3]
	s_waitcnt lgkmcnt(1)
	v_add_f32_e32 v2, v8, v9
	ds_bpermute_b32 v3, v17, v2
	s_waitcnt lgkmcnt(1)
	v_add_f32_e32 v18, v18, v19
	ds_bpermute_b32 v19, v131, v18
	v_pk_mul_f32 v[8:9], v[114:115], v[12:13]
	v_or_b32_e32 v4, v4, v20
	s_waitcnt lgkmcnt(1)
	v_add_f32_e32 v2, v2, v3
	ds_bpermute_b32 v3, v131, v2
	s_waitcnt lgkmcnt(1)
	v_add_f32_e32 v12, v18, v19
	v_mul_f32_e32 v13, 0x3fb8aa3b, v12
	v_fma_f32 v18, v12, s83, -v13
	v_rndne_f32_e32 v19, v13
	v_fmac_f32_e32 v18, 0x32a5705f, v12
	v_sub_f32_e32 v13, v13, v19
	s_waitcnt lgkmcnt(0)
	v_add_f32_e32 v2, v2, v3
	v_add_f32_e32 v3, v13, v18
	v_mul_f32_e32 v13, 0x3fb8aa3b, v2
	v_fma_f32 v18, v2, s83, -v13
	v_rndne_f32_e32 v20, v13
	v_cvt_i32_f32_e32 v19, v19
	v_exp_f32_e32 v3, v3
	v_fmac_f32_e32 v18, 0x32a5705f, v2
	v_sub_f32_e32 v13, v13, v20
	v_add_f32_e32 v13, v13, v18
	v_cvt_i32_f32_e32 v20, v20
	v_exp_f32_e32 v13, v13
	v_ldexp_f32 v3, v3, v19
	v_cmp_ngt_f32_e32 vcc, s84, v12
	v_lshl_add_u64 v[4:5], s[66:67], 0, v[4:5]
	v_pk_mul_f32 v[10:11], v[116:117], v[10:11]
	v_cndmask_b32_e32 v3, 0, v3, vcc
	v_cmp_nlt_f32_e32 vcc, s85, v12
	v_ldexp_f32 v12, v13, v20
	s_nop 0
	v_cndmask_b32_e32 v3, v231, v3, vcc
	v_cmp_ngt_f32_e32 vcc, s84, v2
	s_nop 1
	v_cndmask_b32_e32 v12, 0, v12, vcc
	v_cmp_nlt_f32_e32 vcc, s85, v2
	s_nop 1
	v_cndmask_b32_e32 v2, v231, v12, vcc
	v_sub_f32_e32 v2, v3, v2
	v_add_f32_e32 v12, v130, v2
	v_mov_b32_e32 v13, v12
	v_mov_b32_e32 v2, v12
	v_mov_b32_e32 v3, v12
; __device__ __forceinline__ unsigned pk2(float lo, float hi) { f32x2 v = {lo, hi}; bf16x2_t b = __builtin_convertvector(v, bf16x2_t); return __builtin_bit_cast(unsigned, b); }
; __device__ __forceinline__ float bf_lo(unsigned w) { return __uint_as_float(w << 16); }
; __device__ __forceinline__ float bf_hi(unsigned w) { return __uint_as_float(w & 0xffff0000u); }
; __device__ __forceinline__ void attn_phase(LAS unsigned char* lds, unsigned char* ws, int l) {
;     ...
;     for (int vb = blockIdx.x; vb < 256; vb += gridDim.x) {
;         const int v2 = (vb & 7) * 32 + (vb >> 3);
;         const int j = v2 & 7, h = (v2 >> 3) & 7, b = v2 >> 6;
;         const bf16_t* base = P + (size_t)b * SEQ * INW;
;         for (int i = 0; i < 2; ++i) { const int qblk = i ? (15 - j) : j;
;     ...
;             for (int r = 0; r < 32; ++r) { const size_t t = (size_t)b * SEQ + qblk * 256 + wv * 32 + r;
;                 const u32x2 a = *(const u32x2*)(O12 + t * 4096 + h * 256 + 4 * lane), bb = *(const u32x2*)(O12 + t * 4096 + 2048 + h * 256 + 4 * lane);
;                 f32x4 o = (f32x4){bf_lo(a.x), bf_hi(a.x), bf_lo(a.y), bf_hi(a.y)} - (f32x4){bf_lo(bb.x), bf_hi(bb.x), bf_lo(bb.y), bf_hi(bb.y)} * lam;
;                 const float ss = wave_sum(o[0] * o[0] + o[1] * o[1] + o[2] * o[2] + o[3] * o[3]);
;                 const float rs = 1.0f / sqrtf(ss * (1.0f / 256.0f) + SUBLN_EPS);
;                 o = o * rs * g;
;                 u32x2 w; w.x = pk2(o[0], o[1]); w.y = pk2(o[2], o[3]);
;                 *(u32x2*)(OB + t * DM + h * 256 + 4 * lane) = w; }
.LBB0_285:
	v_add_co_u32_e32 v20, vcc, 0x1000, v6
	global_load_dwordx2 v[18:19], v[6:7], off
	s_nop 0
	v_addc_co_u32_e32 v21, vcc, 0, v7, vcc
	global_load_dwordx2 v[20:21], v[20:21], off
	v_xor_b32_e32 v27, 0x80000000, v3
	v_xor_b32_e32 v26, 0x80000000, v2
	s_waitcnt vmcnt(1)
	v_lshlrev_b32_e32 v22, 16, v18
	v_and_b32_e32 v23, 0xffff0000, v18
	v_lshlrev_b32_e32 v18, 16, v19
	v_and_b32_e32 v19, 0xffff0000, v19
	s_waitcnt vmcnt(0)
	v_lshlrev_b32_e32 v24, 16, v20
	v_and_b32_e32 v25, 0xffff0000, v20
	v_lshlrev_b32_e32 v20, 16, v21
	v_and_b32_e32 v21, 0xffff0000, v21
	v_pk_fma_f32 v[18:19], v[26:27], v[20:21], v[18:19]
	v_pk_fma_f32 v[20:21], v[12:13], v[24:25], v[22:23] neg_lo:[1,0,0] neg_hi:[1,0,0]
	v_pk_mul_f32 v[22:23], v[18:19], v[18:19]
	v_mul_f32_e32 v24, v21, v21
	v_fmac_f32_e32 v24, v20, v20
	v_add_f32_e32 v22, v22, v24
	v_add_f32_e32 v22, v23, v22
	ds_bpermute_b32 v23, v0, v22
	s_waitcnt lgkmcnt(0)
	v_add_f32_e32 v22, v22, v23
	ds_bpermute_b32 v23, v14, v22
	s_waitcnt lgkmcnt(0)
	v_add_f32_e32 v22, v22, v23
	ds_bpermute_b32 v23, v15, v22
	s_waitcnt lgkmcnt(0)
	v_add_f32_e32 v22, v22, v23
	ds_bpermute_b32 v23, v16, v22
	s_waitcnt lgkmcnt(0)
	v_add_f32_e32 v22, v22, v23
	ds_bpermute_b32 v23, v17, v22
	s_waitcnt lgkmcnt(0)
	v_add_f32_e32 v22, v22, v23
	ds_bpermute_b32 v23, v131, v22
	s_waitcnt lgkmcnt(0)
	v_add_f32_e32 v22, v22, v23
	v_fmamk_f32 v22, v22, 0x3b800000, v225
	v_cmp_gt_f32_e32 vcc, s91, v22
	v_mul_f32_e32 v23, 0x4f800000, v22
	s_nop 0
	v_cndmask_b32_e32 v22, v22, v23, vcc
	v_sqrt_f32_e32 v23, v22
	s_nop 0
	v_add_u32_e32 v24, -1, v23
	v_fma_f32 v25, -v24, v23, v22
	v_cmp_ge_f32_e64 s[0:1], 0, v25
	v_add_u32_e32 v25, 1, v23
	s_nop 0
	v_cndmask_b32_e64 v24, v23, v24, s[0:1]
	v_fma_f32 v23, -v25, v23, v22
	v_cmp_lt_f32_e64 s[0:1], 0, v23
	s_nop 1
	v_cndmask_b32_e64 v23, v24, v25, s[0:1]
	v_mul_f32_e32 v24, 0x37800000, v23
	v_cndmask_b32_e32 v23, v23, v24, vcc
	v_cmp_class_f32_e32 vcc, v22, v226
	s_nop 1
	v_cndmask_b32_e32 v22, v23, v22, vcc
	v_div_scale_f32 v23, s[0:1], v22, v22, 1.0
	v_rcp_f32_e32 v24, v23
	s_mov_b64 s[0:1], 0x2000
	v_lshl_add_u64 v[6:7], v[6:7], 0, s[0:1]
	v_fma_f32 v25, -v23, v24, 1.0
	v_fmac_f32_e32 v24, v25, v24
	v_div_scale_f32 v25, vcc, 1.0, v22, 1.0
	v_mul_f32_e32 v26, v25, v24
	v_fma_f32 v27, -v23, v26, v25
	v_fmac_f32_e32 v26, v27, v24
	v_fma_f32 v23, -v23, v26, v25
	v_div_fmas_f32 v23, v23, v24, v26
	v_div_fixup_f32 v22, v23, v22, 1.0
	v_pk_mul_f32 v[20:21], v[20:21], v[22:23] op_sel_hi:[1,0]
	v_pk_mul_f32 v[18:19], v[18:19], v[22:23] op_sel_hi:[1,0]
	v_pk_mul_f32 v[20:21], v[10:11], v[20:21]
	v_pk_mul_f32 v[18:19], v[8:9], v[18:19]
	v_cvt_pk_bf16_f32 v20, v20, v21
	v_cvt_pk_bf16_f32 v21, v18, v19
	v_lshl_add_u64 v[18:19], v[4:5], 0, s[36:37]
	s_add_u32 s36, s36, 0x1000
	s_addc_u32 s37, s37, 0
	s_cmp_eq_u32 s36, 0x10000
	global_store_dwordx2 v[18:19], v[20:21], off
	s_cbranch_scc0 .LBB0_285
	s_add_i32 s98, s98, 1
	s_cmp_lt_u32 s98, 4
	s_cbranch_scc1 .LBB0_249
	v_readlane_b32 s48, v255, 6
	v_readlane_b32 s49, v255, 7
	v_readlane_b32 s93, v255, 12
	s_mov_b32 s40, s50

; __global__ void __launch_bounds__(512, 2) fwd_kernel(Args a) {
;     extern __shared__ __attribute__((aligned(16))) unsigned char smem[];
	.amdhsa_kernel _Z10fwd_kernel4Args
		.amdhsa_group_segment_fixed_size 0
		.amdhsa_private_segment_fixed_size 0
		.amdhsa_kernarg_size 432
		.amdhsa_user_sgpr_count 2
		.amdhsa_user_sgpr_dispatch_ptr 0
		.amdhsa_user_sgpr_queue_ptr 0
		.amdhsa_user_sgpr_kernarg_segment_ptr 1
		.amdhsa_user_sgpr_dispatch_id 0
		.amdhsa_user_sgpr_kernarg_preload_length 0
		.amdhsa_user_sgpr_kernarg_preload_offset 0
		.amdhsa_user_sgpr_private_segment_size 0
		.amdhsa_uses_dynamic_stack 0
		.amdhsa_enable_private_segment 0
		.amdhsa_system_sgpr_workgroup_id_x 1
		.amdhsa_system_sgpr_workgroup_id_y 0
		.amdhsa_system_sgpr_workgroup_id_z 0
		.amdhsa_system_sgpr_workgroup_info 0
		.amdhsa_system_vgpr_workitem_id 2
		.amdhsa_next_free_vgpr 256
		.amdhsa_next_free_sgpr 102
		.amdhsa_accum_offset 256
		.amdhsa_reserve_vcc 1
		.amdhsa_float_round_mode_32 0
		.amdhsa_float_round_mode_16_64 0
		.amdhsa_float_denorm_mode_32 3
		.amdhsa_float_denorm_mode_16_64 3
		.amdhsa_dx10_clamp 1
		.amdhsa_ieee_mode 1
		.amdhsa_fp16_overflow 0
		.amdhsa_tg_split 0
		.amdhsa_exception_fp_ieee_invalid_op 0
		.amdhsa_exception_fp_denorm_src 0
		.amdhsa_exception_fp_ieee_div_zero 0
		.amdhsa_exception_fp_ieee_overflow 0
		.amdhsa_exception_fp_ieee_underflow 0
		.amdhsa_exception_fp_ieee_inexact 0
		.amdhsa_exception_int_div_zero 0
	.end_amdhsa_kernel

; __global__ void __launch_bounds__(512, 2) fwd_kernel(Args a) {
;     extern __shared__ __attribute__((aligned(16))) unsigned char smem[];
amdhsa.kernels:
  - .agpr_count:     0
    .args:
      - .offset:         0
        .size:           176
        .value_kind:     by_value
      - .offset:         176
        .size:           4
        .value_kind:     hidden_block_count_x
      - .offset:         180
        .size:           4
        .value_kind:     hidden_block_count_y
      - .offset:         184
        .size:           4
        .value_kind:     hidden_block_count_z
      - .offset:         188
        .size:           2
        .value_kind:     hidden_group_size_x
      - .offset:         190
        .size:           2
        .value_kind:     hidden_group_size_y
      - .offset:         192
        .size:           2
        .value_kind:     hidden_group_size_z
      - .offset:         194
        .size:           2
        .value_kind:     hidden_remainder_x
      - .offset:         196
        .size:           2
        .value_kind:     hidden_remainder_y
      - .offset:         198
        .size:           2
        .value_kind:     hidden_remainder_z
      - .offset:         216
        .size:           8
        .value_kind:     hidden_global_offset_x
      - .offset:         224
        .size:           8
        .value_kind:     hidden_global_offset_y
      - .offset:         232
        .size:           8
        .value_kind:     hidden_global_offset_z
      - .offset:         240
        .size:           2
        .value_kind:     hidden_grid_dims
      - .offset:         264
        .size:           8
        .value_kind:     hidden_multigrid_sync_arg
      - .offset:         296
        .size:           4
        .value_kind:     hidden_dynamic_lds_size
    .group_segment_fixed_size: 0
    .kernarg_segment_align: 8
    .kernarg_segment_size: 432
    .language:       OpenCL C
    .language_version:
      - 2
      - 0
    .max_flat_workgroup_size: 512
    .name:           _Z10fwd_kernel4Args
    .private_segment_fixed_size: 0
    .sgpr_count:     108
    .sgpr_spill_count: 212
    .symbol:         _Z10fwd_kernel4Args.kd
    .uniform_work_group_size: 1
    .uses_dynamic_stack: false
    .vgpr_count:     256
    .vgpr_spill_count: 0
    .wavefront_size: 64
